# strategy 4 mirror: static s_setprio 1 for the older wave half (waves 0-3), per-segment flips deleted
# baseline (speedup 1.0000x reference)
.LBB0_445:
	s_add_u32 s56, s62, 0xb0080
	s_addc_u32 s57, s63, 0
	s_add_u32 s62, s60, 0x100
	v_mov_b32_e32 v2, 0
	s_addc_u32 s63, s61, 0
	s_mov_b32 s84, -2
	s_waitcnt lgkmcnt(0)
	s_add_i32 s22, 0, 0x10000
	s_add_i32 s23, 0, 0x14000
	v_add_u32_e32 v134, s22, v191
	v_add_u32_e32 v182, s23, v191
	ds_read_b128 v[114:117], v134
	ds_read_b128 v[126:129], v134 offset:1024
	ds_read_b128 v[130:133], v134 offset:2048
	ds_read_b128 v[134:137], v134 offset:3072
	ds_read_b128 v[146:149], v182
	ds_read_b128 v[150:153], v182 offset:1024
	ds_read_b128 v[158:161], v182 offset:2048
	ds_read_b128 v[182:185], v182 offset:3072
	ds_read_b128 v[186:189], v193
	ds_read_b128 v[194:197], v193 offset:1024
	ds_read_b128 v[198:201], v193 offset:2048
	ds_read_b128 v[214:217], v193 offset:3072
	ds_read_b128 v[218:221], v193 offset:4096
	ds_read_b128 v[222:225], v193 offset:5120
	ds_read_b128 v[226:229], v193 offset:6144
	ds_read_b128 v[230:233], v193 offset:7168
	s_mov_b64 s[12:13], 0xb0000
	s_mov_b64 s[86:87], 0x108000
	s_mov_b64 s[96:97], 0x58080
	s_mov_b64 vcc, 0xb0080
	s_mov_b64 s[0:1], 0x108080
	s_cmp_eq_u64 s[40:41], 0
	s_cbranch_scc1 .Lpr_446
	s_setprio 1

.LBB0_487:
	s_ashr_i32 s57, s56, 31
	s_lshl_b64 s[20:21], s[56:57], 19
	s_add_u32 s60, s94, s20
	s_addc_u32 s61, s95, s21
	s_and_b64 s[20:21], s[54:55], exec
	s_cselect_b32 s57, s61, s69
	s_cselect_b32 s86, s60, s68
	s_ashr_i32 s51, s50, 31
	s_lshl_b64 s[20:21], s[50:51], 19
	s_add_u32 s62, s15, s20
	s_addc_u32 s63, s42, s21
	s_and_b64 s[20:21], s[54:55], exec
	s_cselect_b32 s51, s63, s77
	s_cselect_b32 s87, s62, s76
	s_add_u32 s68, s68, 0x40080
	s_addc_u32 s69, s69, 0
	s_add_u32 s91, s76, 0x100
	v_mov_b32_e32 v2, 0
	s_addc_u32 s96, s77, 0
	s_mov_b32 s97, -2
	s_add_i32 s22, 0, 0x10000
	v_add_u32_e32 v152, s22, v139
	s_add_i32 s23, 0, 0x14000
	ds_read_b128 v[134:137], v152
	ds_read_b128 v[144:147], v152 offset:1024
	ds_read_b128 v[148:151], v152 offset:2048
	ds_read_b128 v[152:155], v152 offset:3072
	v_add_u32_e32 v186, s23, v139
	ds_read_b128 v[156:159], v186
	ds_read_b128 v[160:163], v186 offset:1024
	ds_read_b128 v[182:185], v186 offset:2048
	ds_read_b128 v[186:189], v186 offset:3072
	ds_read_b128 v[190:193], v142
	ds_read_b128 v[194:197], v142 offset:1024
	ds_read_b128 v[198:201], v142 offset:2048
	ds_read_b128 v[214:217], v142 offset:3072
	ds_read_b128 v[218:221], v142 offset:4096
	ds_read_b128 v[222:225], v142 offset:5120
	ds_read_b128 v[226:229], v142 offset:6144
	ds_read_b128 v[230:233], v142 offset:7168
	s_cmp_eq_u64 s[48:49], 0
	s_cbranch_scc1 .Lpr_488
	s_setprio 1

.LBB0_603:
	s_ashr_i32 s51, s50, 31
	s_lshl_b64 s[20:21], s[50:51], 18
	s_add_u32 s78, s0, s20
	s_addc_u32 s79, s1, s21
	s_and_b64 s[20:21], s[56:57], exec
	s_cselect_b32 s42, s79, s7
	s_cselect_b32 s43, s78, s6
	s_ashr_i32 s49, s48, 31
	s_lshl_b64 s[20:21], s[48:49], 18
	s_add_u32 s40, s76, s20
	s_addc_u32 s41, s77, s21
	s_and_b64 s[20:21], s[56:57], exec
	s_cselect_b32 s46, s41, s69
	s_cselect_b32 s47, s40, s68
	s_add_u32 s6, s6, 0x20080
	s_addc_u32 s7, s7, 0
	s_add_u32 s49, s68, 0x100
	v_mov_b32_e32 v2, 0
	s_addc_u32 s51, s69, 0
	s_mov_b32 s84, -2
	s_waitcnt lgkmcnt(0)
	s_add_i32 s22, 0, 0x10000
	s_add_i32 s23, 0, 0x14000
	v_add_u32_e32 v150, s22, v139
	v_add_u32_e32 v186, s23, v139
	ds_read_b128 v[134:137], v150
	ds_read_b128 v[142:145], v150 offset:1024
	ds_read_b128 v[146:149], v150 offset:2048
	ds_read_b128 v[150:153], v150 offset:3072
	ds_read_b128 v[154:157], v186
	ds_read_b128 v[158:161], v186 offset:1024
	ds_read_b128 v[182:185], v186 offset:2048
	ds_read_b128 v[186:189], v186 offset:3072
	ds_read_b128 v[190:193], v141
	ds_read_b128 v[194:197], v141 offset:1024
	ds_read_b128 v[198:201], v141 offset:2048
	ds_read_b128 v[214:217], v141 offset:3072
	ds_read_b128 v[218:221], v141 offset:4096
	ds_read_b128 v[222:225], v141 offset:5120
	ds_read_b128 v[226:229], v141 offset:6144
	ds_read_b128 v[230:233], v141 offset:7168
	s_cmp_eq_u64 s[52:53], 0
	s_cbranch_scc1 .Lpr_604
	s_setprio 1

.LBB0_777:
	s_ashr_i32 s61, s60, 31
	s_lshl_b64 s[20:21], s[60:61], 19
	s_add_u32 s62, s94, s20
	s_addc_u32 s63, s95, s21
	s_and_b64 s[20:21], s[56:57], exec
	s_cselect_b32 s61, s63, s77
	s_cselect_b32 s85, s62, s76
	s_ashr_i32 s59, s58, 31
	s_lshl_b64 s[20:21], s[58:59], 19
	s_add_u32 s68, s15, s20
	s_addc_u32 s69, s42, s21
	s_and_b64 s[20:21], s[56:57], exec
	s_cselect_b32 s59, s69, s79
	s_cselect_b32 s86, s68, s78
	s_add_u32 s76, s76, 0x40080
	s_addc_u32 s77, s77, 0
	s_add_u32 s87, s78, 0x100
	v_mov_b32_e32 v2, 0
	s_addc_u32 vcc_lo, s79, 0
	s_mov_b32 vcc_hi, -2
	s_waitcnt lgkmcnt(0)
	s_add_i32 s22, 0, 0x10000
	s_add_i32 s23, 0, 0x14000
	v_add_u32_e32 v142, s22, v193
	v_add_u32_e32 v158, s23, v193
	ds_read_b128 v[130:133], v142
	ds_read_b128 v[134:137], v142 offset:1024
	ds_read_b128 v[138:141], v142 offset:2048
	ds_read_b128 v[142:145], v142 offset:3072
	ds_read_b128 v[146:149], v158
	ds_read_b128 v[150:153], v158 offset:1024
	ds_read_b128 v[154:157], v158 offset:2048
	ds_read_b128 v[158:161], v158 offset:3072
	ds_read_b128 v[184:187], v196
	ds_read_b128 v[188:191], v196 offset:1024
	ds_read_b128 v[198:201], v196 offset:2048
	ds_read_b128 v[214:217], v196 offset:3072
	ds_read_b128 v[218:221], v196 offset:4096
	ds_read_b128 v[222:225], v196 offset:5120
	ds_read_b128 v[226:229], v196 offset:6144
	ds_read_b128 v[230:233], v196 offset:7168
	s_cmp_eq_u64 s[50:51], 0
	s_cbranch_scc1 .Lpr_778
	s_setprio 1

.LBB0_849:
	s_ashr_i32 s79, s78, 31
	s_lshl_b64 s[20:21], s[78:79], 19
	s_add_u32 s88, s4, s20
	s_addc_u32 s89, s5, s21
	s_and_b64 s[20:21], s[54:55], exec
	s_cselect_b32 s76, s89, s57
	s_cselect_b32 s77, s88, s56
	s_ashr_i32 s69, s68, 31
	s_lshl_b64 s[20:21], s[68:69], 19
	v_readlane_b32 s12, v247, 42
	s_add_u32 s94, s12, s20
	v_readlane_b32 s12, v245, 61
	s_addc_u32 s95, s12, s21
	s_and_b64 s[20:21], s[54:55], exec
	s_cselect_b32 s69, s95, s59
	s_cselect_b32 s79, s94, s58
	s_add_u32 s56, s56, 0x40080
	s_addc_u32 s57, s57, 0
	s_add_u32 s86, s58, 0x100
	v_mov_b32_e32 v2, 0
	s_addc_u32 s87, s59, 0
	s_mov_b32 s91, -2
	s_add_i32 vcc_lo, 0, 0x10000
	v_add_u32_e32 v158, vcc_lo, v145
	s_add_i32 vcc_hi, 0, 0x14000
	ds_read_b128 v[138:141], v158
	ds_read_b128 v[146:149], v158 offset:1024
	ds_read_b128 v[150:153], v158 offset:2048
	ds_read_b128 v[158:161], v158 offset:3072
	v_add_u32_e32 v194, vcc_hi, v145
	ds_read_b128 v[182:185], v194
	ds_read_b128 v[186:189], v194 offset:1024
	ds_read_b128 v[190:193], v194 offset:2048
	ds_read_b128 v[194:197], v194 offset:3072
	ds_read_b128 v[198:201], v157
	ds_read_b128 v[214:217], v157 offset:1024
	ds_read_b128 v[218:221], v157 offset:2048
	ds_read_b128 v[222:225], v157 offset:3072
	ds_read_b128 v[226:229], v157 offset:4096
	ds_read_b128 v[230:233], v157 offset:5120
	ds_read_b128 v[234:237], v157 offset:6144
	ds_read_b128 v[238:241], v157 offset:7168
	s_cmp_eq_u64 s[62:63], 0
	s_cbranch_scc1 .Lpr_850
	s_setprio 1
